# retention loop: next-tile LDS-DMA issues interleaved between QK MFMA pairs instead of a burst at the tile top
# speedup vs baseline: 1.0114x; 1.0114x over previous
.LBB0_806:
	s_add_i32 s61, s63, 0x10000
	s_and_b32 s64, s61, 0x10000
	s_add_i32 s64, s36, s64
	s_and_b32 s0, s63, 0x10000
	s_add_i32 s0, s29, s0
	v_add3_u32 v164, s0, v215, v216
	v_xor_b32_e32 v68, 32, v164
	ds_read_b128 v[174:177], v68
	v_xor_b32_e32 v68, 64, v164
	ds_read_b128 v[178:181], v68
	v_xor_b32_e32 v68, 0x60, v164
	ds_read_b128 v[64:67], v164
	ds_read_b128 v[182:185], v68
	s_waitcnt lgkmcnt(0)
	v_mfma_f32_32x32x16_bf16 v[64:79], v[64:67], v[142:145], 0
	v_mfma_f32_32x32x16_bf16 v[64:79], v[174:177], v[138:141], v[64:79]
	s_add_i32 m0, s64, 0x0
	v_lshl_add_u64 v[250:251], s[24:25], 0, v[146:147]
	global_load_lds_dwordx4 v[250:251], off
	v_xor_b32_e32 v165, 0x80, v164
	ds_read_b128 v[174:177], v165
	v_xor_b32_e32 v165, 0xa0, v164
	ds_read_b128 v[224:227], v165
	v_mfma_f32_32x32x16_bf16 v[64:79], v[178:181], v[134:137], v[64:79]
	v_mfma_f32_32x32x16_bf16 v[64:79], v[182:185], v[130:133], v[64:79]
	s_add_i32 m0, s64, 0x400
	v_lshl_add_u64 v[250:251], s[24:25], 0, v[150:151]
	global_load_lds_dwordx4 v[250:251], off
	v_xor_b32_e32 v165, 0xc0, v164
	ds_read_b128 v[178:181], v165
	v_xor_b32_e32 v165, 0xe0, v164
	ds_read_b128 v[182:185], v165
	s_waitcnt lgkmcnt(0)
	v_mfma_f32_32x32x16_bf16 v[64:79], v[174:177], v[126:129], v[64:79]
	v_mfma_f32_32x32x16_bf16 v[64:79], v[224:227], v[122:125], v[64:79]
	s_add_i32 m0, s64, 0x800
	v_lshl_add_u64 v[250:251], s[24:25], 0, v[154:155]
	global_load_lds_dwordx4 v[250:251], off
	v_xor_b32_e32 v165, 0x100, v164
	ds_read_b128 v[174:177], v165
	v_xor_b32_e32 v165, 0x120, v164
	ds_read_b128 v[224:227], v165
	v_mfma_f32_32x32x16_bf16 v[64:79], v[178:181], v[118:121], v[64:79]
	v_mfma_f32_32x32x16_bf16 v[64:79], v[182:185], v[114:117], v[64:79]
	s_add_i32 m0, s64, 0xc00
	v_lshl_add_u64 v[250:251], s[24:25], 0, v[158:159]
	global_load_lds_dwordx4 v[250:251], off
	v_xor_b32_e32 v165, 0x140, v164
	ds_read_b128 v[178:181], v165
	v_xor_b32_e32 v165, 0x160, v164
	ds_read_b128 v[182:185], v165
	s_waitcnt lgkmcnt(0)
	v_mfma_f32_32x32x16_bf16 v[64:79], v[174:177], v[108:111], v[64:79]
	v_mfma_f32_32x32x16_bf16 v[64:79], v[224:227], v[104:107], v[64:79]
	s_lshl_b32 s24, s60, 7
	s_add_u32 s24, s6, s24
	s_addc_u32 s25, s7, 0
	s_add_i32 m0, s64, 0x8000
	v_lshl_add_u64 v[250:251], s[24:25], 0, v[148:149]
	global_load_lds_dwordx4 v[250:251], off
	v_xor_b32_e32 v165, 0x180, v164
	ds_read_b128 v[174:177], v165
	v_xor_b32_e32 v165, 0x1a0, v164
	ds_read_b128 v[224:227], v165
	v_mfma_f32_32x32x16_bf16 v[64:79], v[178:181], v[100:103], v[64:79]
	v_mfma_f32_32x32x16_bf16 v[64:79], v[182:185], v[96:99], v[64:79]
	s_add_i32 m0, s64, 0x8400
	v_lshl_add_u64 v[250:251], s[24:25], 0, v[152:153]
	global_load_lds_dwordx4 v[250:251], off
	v_xor_b32_e32 v165, 0x1c0, v164
	v_xor_b32_e32 v164, 0x1e0, v164
	ds_read_b128 v[178:181], v165
	ds_read_b128 v[182:185], v164
	s_waitcnt lgkmcnt(0)
	v_mfma_f32_32x32x16_bf16 v[64:79], v[174:177], v[92:95], v[64:79]
	v_mfma_f32_32x32x16_bf16 v[64:79], v[224:227], v[88:91], v[64:79]
	s_add_i32 m0, s64, 0x8800
	v_lshl_add_u64 v[250:251], s[24:25], 0, v[156:157]
	global_load_lds_dwordx4 v[250:251], off
	v_mfma_f32_32x32x16_bf16 v[64:79], v[178:181], v[84:87], v[64:79]
	v_mfma_f32_32x32x16_bf16 v[64:79], v[182:185], v[80:83], v[64:79]
	s_add_i32 m0, s64, 0x8c00
	v_lshl_add_u64 v[250:251], s[24:25], 0, v[160:161]
	global_load_lds_dwordx4 v[250:251], off
	s_cmpk_gt_u32 s59, 0xfff
	s_mov_b64 s[24:25], -1
	s_cbranch_scc0 .LBB0_808
	s_and_b32 s1, s62, 0x1fffffc
	s_cmp_eq_u32 s1, 64
	s_cselect_b64 vcc, -1, 0
	v_cndmask_b32_e32 v164, v214, v218, vcc
	v_exp_f32_e32 v188, v164
	s_mov_b64 s[24:25], 0
	s_nop 2
	v_pk_mul_f32 v[174:175], v[188:189], v[64:65] op_sel_hi:[0,1]
	v_pk_mul_f32 v[176:177], v[188:189], v[66:67] op_sel_hi:[0,1]
	v_pk_mul_f32 v[178:179], v[188:189], v[68:69] op_sel_hi:[0,1]
	v_pk_mul_f32 v[180:181], v[188:189], v[70:71] op_sel_hi:[0,1]
	v_pk_mul_f32 v[182:183], v[188:189], v[72:73] op_sel_hi:[0,1]
	v_pk_mul_f32 v[184:185], v[188:189], v[74:75] op_sel_hi:[0,1]
	v_pk_mul_f32 v[186:187], v[188:189], v[76:77] op_sel_hi:[0,1]
	v_mul_f32_e32 v194, v188, v78
